# scan tasks permuted so the two value-half chains of one (batch, head, direction) share an XCD
# speedup vs baseline: 1.0097x; 1.0022x over previous
; #define LAS __attribute__((address_space(3)))
; DI const float* inp(int i) { return as_global<const float>(ld_ptr(i)); }
; DI float* ev_ptr(unsigned char* ws, int chunk, int h, int dir) { return (float*)(ws + WS_EV) + ((size_t)(chunk * NH + h) * 2 + dir) * 384; }
; DI void phase_scan(int l, int wv, bool fill, bool last) {
;     const Frame F = mkframe(wv);
;     const float* pu = inp(I_PU) + (size_t)l * NEXP * D; const float* pv = inp(I_PV) + (size_t)l * NEXP * D;
;     constexpr int RS = 272, RS64 = 144;
;     constexpr int O_QT = 0, O_KT = 17408, O_ST = 34816, O_V = 52224, O_PM = 61440, O_EV = 70656;
;     LAS unsigned char* L = F.lds;
;     const int tid = F.tid, lane = F.lane, w = F.wave, r32 = lane & 31, hh = lane >> 5;
;     const int srow = tid >> 3, sc16 = (tid & 7) * 16, svc = (tid & 7) * 8;
;     for (int task = blockIdx.x; task < NBATCH * NH * 4; task += F.G) {
;         const int b = task >> 5, h = (task >> 2) & 7, dir = (task >> 1) & 1, vh = task & 1;
;         const int cq = (dir ? C_QTB : C_QTF) + h * DK + sc16, ck = (dir ? C_KTB : C_KTF) + h * DK + sc16, cvv = C_VI + h * DK + vh * 64 + svc;
;         f32x16 S;
; #pragma unroll
;         for (int i = 0; i < 16; ++i) S[i] = 0.f;
;         auto chunk_row0 = [&](int c) { return c < 4 ? NLAT + b * CTXL + (dir ? 3 - c : c) * 64 : b * SEQ + (dir ? 35 - c : c - 4) * 64; };
;         u32x4 q0, q1, k0, k1, vr; f32x4 evr = (f32x4){0.f, 0.f, 0.f, 0.f};
;         f32x4 fx[8]; const int fidx = (int)blockIdx.x * 4 + w; const bool filler = fill && w < 4;
;         auto fill_load = [&](int it) { const float* src = ((it & 1) ? pv : pu) + (size_t)(it >> 1) * D; const float* src2 = src + 1024;
;             unsigned lo = (unsigned)lane * 4u; asm volatile("" : "+v"(lo));
; #pragma unroll
;             for (int c8 = 0; c8 < 4; ++c8) { fx[c8] = __builtin_nontemporal_load((const f32x4*)(src + lo + c8 * 256)); fx[4 + c8] = __builtin_nontemporal_load((const f32x4*)(src2 + lo + c8 * 256)); } };
;         if (filler) fill_load(fidx);
;         {   const int row0 = chunk_row0(0); const bf16* pr = F.PROJ + (size_t)(row0 + srow) * INW;
;             q0 = *(const u32x4*)(pr + cq); q1 = *(const u32x4*)(pr + cq + 8); k0 = *(const u32x4*)(pr + ck); k1 = *(const u32x4*)(pr + ck + 8); vr = *(const u32x4*)(pr + cvv);
;             if (tid < 96) evr = *(const f32x4*)(ev_ptr(F.ws, row0 >> 6, h, dir) + tid * 4); }
.LBB0_470:
	s_andn2_b64 vcc, exec, s[0:1]
	s_cbranch_vccnz .LBB0_562
	s_waitcnt vmcnt(0)
	v_mov_b32_e32 v0, v129
	v_readlane_b32 s0, v253, 54
	v_mbcnt_lo_u32_b32 v0, -1, v0
	v_mbcnt_hi_u32_b32 v1, -1, v0
	s_mov_b32 s2, s88
	v_mov_b32_e32 v0, s0
	ds_read_b64 v[2:3], v0
	v_mov_b32_e32 v0, s79
	v_readlane_b32 s0, v253, 62
	s_waitcnt lgkmcnt(0)
	ds_read_b64 v[2:3], v0
	v_readlane_b32 s6, v253, 31
	v_mov_b32_e32 v0, s0
	v_readlane_b32 s0, v253, 63
	ds_read_b64 v[4:5], v0
	v_writelane_b32 v254, s92, 36
	v_mov_b32_e32 v0, s0
	ds_read_b64 v[6:7], v0
	v_readlane_b32 s7, v253, 32
	v_writelane_b32 v254, s93, 37
	s_waitcnt lgkmcnt(2)
	v_readfirstlane_b32 s1, v3
	v_readfirstlane_b32 s0, v2
	s_waitcnt lgkmcnt(1)
	v_readfirstlane_b32 s3, v5
	v_readfirstlane_b32 s4, v4
	s_waitcnt lgkmcnt(0)
	v_readfirstlane_b32 s5, v7
	s_andn2_b64 vcc, exec, s[6:7]
	v_readfirstlane_b32 s6, v6
	s_cbranch_vccnz .LBB0_509
	v_readlane_b32 s8, v254, 28
	v_readlane_b32 s9, v254, 29
	s_load_dword s7, s[8:9], 0x0
	s_add_u32 s48, s0, 0x1ec00000
	s_addc_u32 s49, s1, 0
	s_add_u32 s8, s0, 0x39c00000
	v_writelane_b32 v254, s8, 38
	s_addc_u32 s8, s1, 0
	v_writelane_b32 v254, s8, 39
	s_waitcnt lgkmcnt(0)
	v_writelane_b32 v254, s7, 40
	s_cmpk_eq_i32 s7, 0x100
	v_readlane_b32 s10, v254, 36
	v_readlane_b32 s7, v253, 27
	s_cselect_b64 s[8:9], -1, 0
	s_lshl_b32 s76, s10, 25
	s_add_i32 s67, s2, s7
	s_cmp_lt_i32 s2, 4
	s_cselect_b64 s[54:55], -1, 0
	s_and_b64 s[56:57], s[8:9], s[54:55]
	s_and_b32 s7, s2, 1
	s_lshl_b64 s[8:9], s[76:77], 2
	s_cmp_eq_u32 s7, 0
	s_cselect_b32 s3, s3, s5
	s_cselect_b32 s4, s4, s6
	s_mov_b32 s5, 0x4c00000
	s_cselect_b32 s6, s5, 0x8c00000
	s_add_u32 s68, s4, s8
	s_addc_u32 s69, s3, s9
	s_ashr_i32 s4, s67, 1
	s_ashr_i32 s5, s4, 31
	s_lshl_b64 s[4:5], s[4:5], 13
	s_add_u32 s4, s68, s4
	s_addc_u32 s5, s69, s5
	v_readlane_b32 s11, v254, 37
	s_add_u32 s8, s4, 0x1000
	v_writelane_b32 v254, s4, 41
	s_addc_u32 s9, s5, 0
	v_lshl_add_u32 v4, s2, 6, v1
	v_writelane_b32 v254, s5, 42
	v_writelane_b32 v254, s8, 43
	s_movk_i32 s3, 0x60
	v_cmp_gt_i32_e64 s[36:37], s3, v4
	v_writelane_b32 v254, s9, 44
	s_lshl_b32 s8, s2, 4
	s_movk_i32 s3, 0x5f
	s_and_b32 s9, s8, 0xffffffe0
	v_cmp_lt_i32_e64 s[4:5], s3, v4
	s_lshl_b32 s3, s9, 2
	v_ashrrev_i32_e32 v7, 5, v1
	s_add_i32 s3, s3, 0
	v_lshlrev_b32_e32 v2, 2, v4
	s_add_i32 s3, s3, 0x11400
	v_lshlrev_b32_e32 v188, 4, v7
	v_and_b32_e32 v0, 31, v1
	v_writelane_b32 v254, s4, 45
	v_ashrrev_i32_e32 v3, 31, v2
	v_add_u32_e32 v189, s3, v188
	s_lshl_b32 s3, s7, 5
	v_ashrrev_i32_e32 v184, 3, v4
	v_writelane_b32 v254, s5, 46
	v_lshl_add_u64 v[2:3], v[2:3], 2, s[0:1]
	s_mov_b64 s[4:5], 0x42c00000
	s_movk_i32 s11, 0x110
	v_or_b32_e32 v12, s3, v0
	v_lshlrev_b32_e32 v187, 2, v1
	v_lshl_add_u64 v[120:121], v[2:3], 0, s[4:5]
	v_mul_lo_u32 v2, v184, s11
	v_mad_u32_u24 v13, v12, s11, 0
	s_movk_i32 s4, 0xfef2
	v_add_u32_e32 v8, 0, v2
	v_and_b32_e32 v2, 16, v1
	v_and_b32_e32 v3, 12, v187
	v_mad_i32_i24 v190, v12, s4, v13
	s_add_u32 s4, s0, s6
	v_or3_b32 v17, v2, s9, v3
	v_or3_b32 v2, v2, s3, v3
	s_addc_u32 s5, s1, 0
	v_lshl_add_u32 v18, v2, 1, 0
	v_ashrrev_i32_e32 v19, 3, v1
	v_mov_b64_e32 v[2:3], s[4:5]
	v_mad_i64_i32 v[2:3], s[4:5], v19, s50, v[2:3]
	s_lshl_b32 s4, s7, 16
	s_add_u32 s0, s0, s4
	s_addc_u32 s1, s1, 0
	s_add_u32 s70, s0, 0x4b00000
	s_addc_u32 s71, s1, 0
	v_and_b32_e32 v5, 7, v1
	v_lshlrev_b32_e32 v11, 2, v7
	s_cmp_gt_i32 s2, 3
	v_add_u32_e32 v14, s9, v11
	v_mul_u32_u24_e32 v128, 24, v5
	s_cselect_b64 s[58:59], -1, 0
	s_sub_i32 s0, s9, 64
	v_lshlrev_b32_e32 v15, 4, v4
	v_lshlrev_b32_e32 v4, 3, v7
	v_bfe_u32 v7, v1, 2, 2
	v_lshl_add_u64 v[122:123], v[2:3], 0, v[128:129]
	v_cmp_eq_u32_e64 s[40:41], 0, v1
	v_or_b32_e32 v1, s0, v0
	v_add_u32_e32 v2, s0, v11
	v_cmp_ge_i32_e64 s[0:1], v12, v14
	v_or_b32_e32 v3, 1, v14
	s_movk_i32 s10, 0x90
	v_writelane_b32 v254, s0, 47
	v_mul_lo_u32 v20, v3, s10
	v_lshlrev_b32_e32 v185, 4, v5
	v_writelane_b32 v254, s1, 48
	v_cmp_le_i32_e64 s[0:1], v12, v14
	v_lshlrev_b32_e32 v186, 3, v5
	v_lshlrev_b32_e32 v9, 5, v5
	v_writelane_b32 v254, s0, 49
	v_mul_u32_u24_e32 v5, 0x110, v0
	v_or_b32_e32 v16, v4, v7
	v_writelane_b32 v254, s1, 50
	v_cmp_ge_i32_e64 s[0:1], v12, v3
	v_mul_lo_u32 v1, v1, s10
	v_mul_lo_u32 v192, v14, s10
	v_writelane_b32 v254, s0, 51
	v_add_u32_e32 v6, 0, v185
	v_mul_lo_u32 v10, v184, s10
	v_writelane_b32 v254, s1, 52
	v_cmp_le_i32_e64 s[0:1], v12, v3
	v_or_b32_e32 v3, 2, v14
	v_mul_lo_u32 v21, v3, s10
	v_writelane_b32 v254, s0, 53
	v_lshl_add_u32 v17, v17, 1, 0
	v_add_u32_e32 v191, 0, v1
	v_writelane_b32 v254, s1, 54
	v_cmp_ge_i32_e64 s[0:1], v12, v3
	v_lshlrev_b32_e32 v1, 1, v14
	v_mul_lo_u32 v19, v16, s11
	v_writelane_b32 v254, s0, 55
	v_mul_lo_u32 v16, v16, s10
	v_add_u32_e32 v23, 0x480, v192
	v_writelane_b32 v254, s1, 56
	v_cmp_le_i32_e64 s[0:1], v12, v3
	v_or_b32_e32 v3, 3, v14
	v_mul_lo_u32 v22, v3, s10
	v_writelane_b32 v254, s0, 57
	v_add_u32_e32 v24, 0x510, v192
	v_add_u32_e32 v25, 0x5a0, v192
	v_writelane_b32 v254, s1, 58
	v_cmp_ge_i32_e64 s[0:1], v12, v3
	v_lshlrev_b32_e32 v158, 1, v0
	v_add_u32_e32 v0, 0, v15
	v_writelane_b32 v254, s0, 59
	s_lshl_b32 s72, s3, 1
	v_add_u32_e32 v197, v8, v9
	v_writelane_b32 v254, s1, 60
	v_cmp_le_i32_e64 s[0:1], v12, v3
	v_add_u32_e32 v3, 8, v14
	v_add_u32_e32 v198, v6, v10
	v_writelane_b32 v254, s0, 61
	v_add_u32_e32 v199, 0x11400, v0
	v_add_u32_e32 v200, v13, v1
	v_writelane_b32 v254, s1, 62
	v_cmp_ge_i32_e64 s[0:1], v12, v3
	v_add_u32_e32 v201, v17, v19
	v_add_u32_e32 v202, v190, v20
	v_writelane_b32 v254, s0, 63
	v_add_u32_e32 v203, v190, v21
	v_add_u32_e32 v204, v190, v22
; #define LAS __attribute__((address_space(3)))
; DI void phase_scan(int l, int wv, bool fill, bool last) {
;     ...
;     for (int task = blockIdx.x; task < NBATCH * NH * 4; task += F.G) {
;         const int b = task >> 5, h = (task >> 2) & 7, dir = (task >> 1) & 1, vh = task & 1;
;     ...
; #pragma unroll
;                 for (int i = 0; i < 16; ++i) { const int t = tb * 32 + (i & 3) + 8 * (i >> 2) + 4 * hh, sp = sb * 32 + r32; const bool keep = dir ? (sp >= t) : (sp <= t);
;                     *(LAS unsigned short*)(L + O_PM + t * RS64 + sp * 2) = f2bf1(keep ? acc[i] : 0.f); }
;             }
;             __syncthreads();
;             if (filler && c < 32) {
;                 const int it = fidx + 1024 * c, e = it >> 1; unsigned char* dst = (it & 1) ? (unsigned char*)F.V : (unsigned char*)F.U;
;                 float am = 0.f;
; #pragma unroll
;                 for (int c8 = 0; c8 < 8; ++c8) am = fmaxf(am, fmaxf(fmaxf(fabsf(fx[c8].x), fabsf(fx[c8].y)), fmaxf(fabsf(fx[c8].z), fabsf(fx[c8].w))));
; #pragma unroll
;                 for (int o = 1; o < 64; o <<= 1) am = fmaxf(am, __shfl_xor(am, o));
;                 const float inv = am > 0.f ? 7.0f / am : 0.f, sc = am > 0.f ? am * (1.0f / 7.0f) : 0.f;
;                 v32h hx;
; #pragma unroll
;                 for (int c8 = 0; c8 < 8; ++c8) { hx[c8 * 4 + 0] = (_Float16)(fx[c8].x * inv); hx[c8 * 4 + 1] = (_Float16)(fx[c8].y * inv); hx[c8 * 4 + 2] = (_Float16)(fx[c8].z * inv); hx[c8 * 4 + 3] = (_Float16)(fx[c8].w * inv); }
;                 const v6i p = __builtin_amdgcn_cvt_scalef32_pk32_fp6_f16(hx, 1.0f);
;                 eseg_store(dst, e, lane, p);
;                 if (lane == 0) ((float*)(F.ws + WS_ESCALE) + ((it & 1) ? NEXP : 0))[e] = sc;
;                 if (c + 1 < 32) fill_load(it + 1024);
;             }
;             if (w >= 4 && outp) {
;                 const int tb = (w - 4) >> 1, vb = (w - 4) & 1;
;                 f32x16 acc;
; #pragma unroll
;                 for (int i = 0; i < 16; ++i) acc[i] = 0.f;
; #pragma unroll
;                 for (int ks = 0; ks < 4; ++ks) { const bf16x8v a = *(const LAS bf16x8v*)(L + O_PM + (tb * 32 + r32) * RS64 + (ks * 16 + 8 * hh) * 2), bv = tr_frag(L + O_V, RS64, ks * 16 + 8 * hh, vb * 32, lane);
;                     acc = __builtin_amdgcn_mfma_f32_32x32x16_bf16(a, bv, acc, 0, 0, 0); }
; #pragma unroll 4
	v_writelane_b32 v255, s1, 0
	v_cmp_le_i32_e64 s[0:1], v12, v3
	v_add_u32_e32 v3, 9, v14
	v_add_u32_e32 v205, v190, v23
	v_writelane_b32 v255, s0, 1
	v_add_u32_e32 v214, v190, v24
	v_add_u32_e32 v215, v190, v25
	v_writelane_b32 v255, s1, 2
	v_cmp_ge_i32_e64 s[0:1], v12, v3
	v_add_u32_e32 v231, v18, v16
	s_nop 0
	v_writelane_b32 v255, s0, 3
	s_nop 1
	v_writelane_b32 v255, s1, 4
	v_cmp_le_i32_e64 s[0:1], v12, v3
	v_add_u32_e32 v3, 10, v14
	s_nop 0
	v_writelane_b32 v255, s0, 5
	s_nop 1
	v_writelane_b32 v255, s1, 6
	v_cmp_ge_i32_e64 s[0:1], v12, v3
	s_nop 1
	v_writelane_b32 v255, s0, 7
	s_nop 1
	v_writelane_b32 v255, s1, 8
	v_cmp_le_i32_e64 s[0:1], v12, v3
	v_add_u32_e32 v3, 11, v14
	v_add_u32_e32 v14, 0x630, v192
	v_writelane_b32 v255, s0, 9
	v_add_u32_e32 v216, v190, v14
	s_nop 0
	v_writelane_b32 v255, s1, 10
	v_cmp_ge_i32_e64 s[0:1], v12, v3
	s_nop 1
	v_writelane_b32 v255, s0, 11
	s_nop 1
	v_writelane_b32 v255, s1, 12
	v_cmp_le_i32_e64 s[0:1], v12, v3
	s_nop 1
	v_writelane_b32 v255, s0, 13
	s_nop 1
	v_writelane_b32 v255, s1, 14
	s_or_b32 s0, s8, 16
	v_add_u32_e32 v3, s0, v11
	v_cmp_ge_i32_e64 s[0:1], v12, v3
	v_mul_lo_u32 v26, v3, s10
	v_add_u32_e32 v217, v190, v26
	v_writelane_b32 v255, s0, 15
	s_nop 1
	v_writelane_b32 v255, s1, 16
	v_cmp_le_i32_e64 s[0:1], v12, v3
	s_nop 1
	v_writelane_b32 v255, s0, 17
	s_nop 1
	v_writelane_b32 v255, s1, 18
	s_or_b32 s0, s8, 17
	v_add_u32_e32 v3, s0, v11
	v_cmp_ge_i32_e64 s[0:1], v12, v3
	v_mul_lo_u32 v27, v3, s10
	v_add_u32_e32 v218, v190, v27
	v_writelane_b32 v255, s0, 19
	s_nop 1
	v_writelane_b32 v255, s1, 20
	v_cmp_le_i32_e64 s[0:1], v12, v3
	s_nop 1
	v_writelane_b32 v255, s0, 21
	s_nop 1
	v_writelane_b32 v255, s1, 22
	s_or_b32 s0, s8, 18
	v_add_u32_e32 v3, s0, v11
	s_or_b32 s0, s8, 19
	v_add_u32_e32 v28, s0, v11
	s_or_b32 s0, s8, 24
	v_add_u32_e32 v29, s0, v11
	s_or_b32 s0, s8, 25
	v_add_u32_e32 v30, s0, v11
	s_or_b32 s0, s8, 26
	v_add_u32_e32 v31, s0, v11
	v_cmp_ge_i32_e64 s[0:1], v12, v3
	v_mul_lo_u32 v33, v3, s10
	v_mul_lo_u32 v34, v28, s10
	v_writelane_b32 v255, s0, 23
	v_mul_lo_u32 v35, v29, s10
	v_mul_lo_u32 v36, v30, s10
	v_writelane_b32 v255, s1, 24
	s_or_b32 s0, s8, 27
	v_add_u32_e32 v11, s0, v11
	s_lshr_b32 s0, s2, 1
	s_mulk_i32 s0, 0x2200
	v_add3_u32 v32, s0, v5, v188
	v_cmp_le_i32_e64 s[0:1], v12, v3
	v_add_u32_e32 v3, 16, v4
	v_lshlrev_b32_e32 v39, 1, v3
	v_or_b32_e32 v3, v3, v7
	v_mul_lo_u32 v40, v3, s10
	v_add_u32_e32 v3, 32, v4
	v_lshlrev_b32_e32 v41, 1, v3
	v_or_b32_e32 v3, v3, v7
	v_mul_lo_u32 v42, v3, s10
	v_add_u32_e32 v3, 48, v4
	v_or_b32_e32 v4, 1, v2
	v_ashrrev_i32_e32 v5, 31, v4
	v_lshlrev_b64 v[126:127], 11, v[4:5]
	v_or_b32_e32 v4, 2, v2
	v_ashrrev_i32_e32 v5, 31, v4
	v_lshlrev_b64 v[130:131], 11, v[4:5]
	v_or_b32_e32 v4, 3, v2
	v_ashrrev_i32_e32 v5, 31, v4
	v_lshlrev_b64 v[132:133], 11, v[4:5]
	v_add_u32_e32 v4, 8, v2
	v_ashrrev_i32_e32 v5, 31, v4
	v_lshlrev_b64 v[134:135], 11, v[4:5]
	v_add_u32_e32 v4, 9, v2
	v_ashrrev_i32_e32 v5, 31, v4
	v_lshlrev_b64 v[136:137], 11, v[4:5]
	v_add_u32_e32 v4, 10, v2
	v_ashrrev_i32_e32 v5, 31, v4
	v_lshlrev_b64 v[138:139], 11, v[4:5]
	v_add_u32_e32 v4, 11, v2
	v_ashrrev_i32_e32 v5, 31, v4
	v_lshlrev_b64 v[140:141], 11, v[4:5]
	v_add_u32_e32 v4, 16, v2
	v_ashrrev_i32_e32 v5, 31, v4
	v_lshlrev_b64 v[142:143], 11, v[4:5]
	v_add_u32_e32 v4, 17, v2
	v_ashrrev_i32_e32 v5, 31, v4
	v_lshlrev_b64 v[144:145], 11, v[4:5]
	v_add_u32_e32 v4, 18, v2
	v_ashrrev_i32_e32 v5, 31, v4
	v_lshlrev_b64 v[146:147], 11, v[4:5]
	v_add_u32_e32 v4, 19, v2
	v_ashrrev_i32_e32 v5, 31, v4
	v_lshlrev_b64 v[148:149], 11, v[4:5]
	v_add_u32_e32 v4, 24, v2
	v_ashrrev_i32_e32 v5, 31, v4
	v_lshlrev_b32_e32 v43, 1, v3
	v_or_b32_e32 v3, v3, v7
	v_lshlrev_b64 v[150:151], 11, v[4:5]
	v_add_u32_e32 v4, 25, v2
	v_mul_lo_u32 v7, v3, s10
	v_ashrrev_i32_e32 v3, 31, v2
	v_ashrrev_i32_e32 v5, 31, v4
	v_lshlrev_b64 v[124:125], 11, v[2:3]
	v_lshlrev_b64 v[152:153], 11, v[4:5]
	v_add_u32_e32 v4, 26, v2
	v_add_u32_e32 v2, 27, v2
	v_writelane_b32 v255, s0, 25
	v_ashrrev_i32_e32 v3, 31, v2
	v_lshlrev_b64 v[156:157], 11, v[2:3]
	v_writelane_b32 v255, s1, 26
	v_mad_u32_u24 v2, v12, s11, v188
	v_readlane_b32 s0, v254, 9
	v_mul_lo_u32 v37, v31, s10
	v_mul_lo_u32 v38, v11, s10
	v_add_u32_e32 v193, s0, v2
	v_readlane_b32 s0, v254, 10
	v_ashrrev_i32_e32 v5, 31, v4
	v_lshlrev_b64 v[154:155], 11, v[4:5]
	v_add_u32_e32 v195, s0, v2
	v_readlane_b32 s0, v254, 11
	v_add_u32_e32 v194, 0, v32
	v_add_u32_e32 v219, v190, v33
	v_add_u32_e32 v196, s0, v32
	v_readlane_b32 s0, v254, 19
	v_readlane_b32 s1, v254, 20
	v_add_u32_e32 v220, v190, v34
	v_add_u32_e32 v221, v190, v35
	v_add_u32_e32 v222, v190, v36
	v_add_u32_e32 v223, v190, v37
	v_add_u32_e32 v224, v190, v38
	v_add_u32_e32 v225, v191, v39
	v_add_u32_e32 v226, v18, v40
	v_add_u32_e32 v227, v191, v41
	v_add_u32_e32 v228, v18, v42
	v_add_u32_e32 v229, v191, v43
	v_add_u32_e32 v230, v18, v7
	s_mov_b32 s73, s0
	v_readlane_b32 s76, v254, 40
	s_nop 3
	s_cmpk_lg_i32 s76, 0x100
	s_cbranch_scc1 .Lscan_noremap
	s_and_b32 s74, s0, 7
	s_lshr_b32 s76, s0, 4
	s_lshl_b32 s76, s76, 3
	s_or_b32 s74, s74, s76
	s_lshl_b32 s74, s74, 1
	s_bfe_u32 s76, s0, 0x10003
	s_or_b32 s73, s74, s76
.Lscan_noremap:
	v_cmp_ge_i32_e64 s[86:87], v12, v28
	v_cmp_le_i32_e64 s[88:89], v12, v28
	v_cmp_ge_i32_e64 s[90:91], v12, v29
	v_cmp_le_i32_e64 s[92:93], v12, v29
	v_cmp_ge_i32_e64 s[94:95], v12, v30
	v_cmp_le_i32_e64 s[96:97], v12, v30
	v_cmp_ge_i32_e64 s[0:1], v12, v31
	v_cmp_le_i32_e64 s[4:5], v12, v31
	v_cmp_ge_i32_e64 s[6:7], v12, v11
	v_cmp_le_i32_e64 s[8:9], v12, v11
	s_branch .LBB0_474
